# MLA attention inner loop: K/V LDS reads issued up-front into free VGPRs with counted lgkmcnt waits; V tile prefetched during softmax
# baseline (speedup 1.0000x reference)
; template <int MODE> __device__ __forceinline__ void attn_unit(const Unit& a, char* shm) {
;     ...
;             const lds_cptr kp = shm3 + LDS_K + s * KSLOT + hi * 1024 + r32 * 16;
;             f32x16 p0 = negm, p1 = negm;
; #pragma unroll
;             for (int d0 = 0; d0 < ND; ++d0) {
;                 const bf16x8 b0 = *(const LAS bf16x8*)(kp + d0 * 2048), b1 = *(const LAS bf16x8*)(kp + d0 * 2048 + 512);
;                 p0 = __builtin_amdgcn_mfma_f32_32x32x16_bf16(b0, qr[d0], p0, 0, 0, 0);
;                 p1 = __builtin_amdgcn_mfma_f32_32x32x16_bf16(b1, qr[d0], p1, 0, 0, 0);
;             }
;             if (MODE == 1) {
; #pragma unroll
;                 for (int r = 0; r < 16; ++r) { const int ks = 64 * t + crow(r, hi); const int r0 = abs(tq - ks), r1 = abs(tq - ks - 32);
;                     p0[r] = (r0 <= 128) ? p0[r] - a.slope2 * (float)r0 : -INFINITY; p1[r] = (r1 <= 128) ? p1[r] - a.slope2 * (float)r1 : -INFINITY; }
;             }
;     ...
;             float ra = MX3(p0[0], p0[1], p1[0]), rb = MX3(p0[2], p0[3], p1[1]); ra = MX3(ra, p1[2], p1[3]);
; #pragma unroll
;             for (int r = 4; r < 16; r += 4) { ra = MX3(ra, p0[r], p0[r + 1]); rb = MX3(rb, p0[r + 2], p0[r + 3]); ra = MX3(ra, p1[r], p1[r + 1]); rb = MX3(rb, p1[r + 2], p1[r + 3]); }
;     ...
;             float rm = halfmax(__builtin_fmaxf(ra, rb));
;             const bool first = (MODE == 0) && (t == a.t_lo);
;             if (first || __any(rm > THR)) {
;                 const float dl = first ? rm : fmaxf(rm, 0.f);
;                 mhat += dl;
; #pragma unroll
;                 for (int r = 0; r < 16; ++r) { p0[r] -= dl; p1[r] -= dl; negm[r] = -mhat; }
;                 if (!first) {
;                     const float f = __builtin_amdgcn_exp2f(-dl); l_reg *= f;
;                     if (hi == 0) wsf[r32] = f;
; #pragma unroll
;                     for (int r = 0; r < 16; ++r) { const float fr_ = wsf[crow(r, hi)]; o[0][r] *= fr_; o[1][r] *= fr_; }
;                 }
;             }
; #pragma unroll
;             for (int r = 0; r < 16; ++r) { p0[r] = __builtin_amdgcn_exp2f(p0[r]); p1[r] = __builtin_amdgcn_exp2f(p1[r]); }
;             f32x2 s2a = (f32x2){p0[0], p0[1]}, s2b = (f32x2){p1[0], p1[1]};
; #pragma unroll
;             for (int k2 = 1; k2 < 8; ++k2) { s2a += (f32x2){p0[2 * k2], p0[2 * k2 + 1]}; s2b += (f32x2){p1[2 * k2], p1[2 * k2 + 1]}; }
;             s2a += s2b;
.LBB0_1907:
	s_cmpk_gt_u32 s34, 0xff
	s_cselect_b64 s[2:3], -1, 0
	s_cmpk_lt_u32 s34, 0x100
	s_cselect_b64 s[44:45], -1, 0
	s_cmp_lg_u32 0, -1
	s_cselect_b32 s1, 0, 0
	v_lshlrev_b32_e32 v0, 10, v145
	v_lshlrev_b32_e32 v1, 4, v144
	s_add_i32 s0, s1, s0
	v_add3_u32 v146, 0, v0, v1
	v_lshl_add_u64 v[0:1], v[38:39], 0, s[6:7]
	s_add_i32 s0, s0, 0x8000
	s_mov_b32 s1, m0
	s_mov_b32 m0, s0
	s_nop 0
	global_load_lds_dwordx4 v[0:1], off
	s_mov_b32 m0, s1
	ds_read_b128 v[40:43], v146
	ds_read_b128 v[44:47], v146 offset:512
	s_mov_b32 s61, s60
	s_mov_b32 s62, s60
	s_mov_b32 s63, s60
	s_mov_b32 s64, s60
	s_mov_b32 s65, s60
	s_mov_b32 s66, s60
	s_mov_b32 s67, s60
	s_mov_b32 s68, s60
	s_mov_b32 s69, s60
	s_mov_b32 s70, s60
	s_mov_b32 s71, s60
	s_mov_b32 s72, s60
	s_mov_b32 s73, s60
	s_mov_b32 s74, s60
	s_mov_b32 s75, s60
	v_mov_b64_e32 v[0:1], s[60:61]
	v_mov_b64_e32 v[2:3], s[62:63]
	v_mov_b64_e32 v[4:5], s[64:65]
	v_mov_b64_e32 v[6:7], s[66:67]
	v_mov_b64_e32 v[8:9], s[68:69]
	v_mov_b64_e32 v[10:11], s[70:71]
	v_mov_b64_e32 v[12:13], s[72:73]
	v_mov_b64_e32 v[14:15], s[74:75]
	v_lshlrev_b32_e32 v48, 1, v32
	v_and_b32_e32 v48, 32, v48
	s_waitcnt vmcnt(0) lgkmcnt(0)
	v_mfma_f32_32x32x16_bf16 v[16:31], v[40:43], v[82:85], v[0:15]
	v_lshlrev_b32_e32 v32, 4, v32
	v_add3_u32 v33, 0, v48, v33
	v_and_b32_e32 v32, 0xc0, v32
	s_and_b64 vcc, exec, s[2:3]
	v_mfma_f32_32x32x16_bf16 v[0:15], v[44:47], v[82:85], v[0:15]
	ds_read_b128 v[40:43], v146 offset:2048
	ds_read_b128 v[44:47], v146 offset:2560
	s_waitcnt lgkmcnt(1)
	v_mfma_f32_32x32x16_bf16 v[16:31], v[40:43], v[86:89], v[16:31]
	s_waitcnt lgkmcnt(0)
	v_mfma_f32_32x32x16_bf16 v[0:15], v[44:47], v[86:89], v[0:15]
	ds_read_b128 v[40:43], v146 offset:4096
	ds_read_b128 v[44:47], v146 offset:4608
	s_waitcnt lgkmcnt(1)
	v_mfma_f32_32x32x16_bf16 v[16:31], v[40:43], v[90:93], v[16:31]
	s_waitcnt lgkmcnt(0)
	v_mfma_f32_32x32x16_bf16 v[0:15], v[44:47], v[90:93], v[0:15]
	ds_read_b128 v[40:43], v146 offset:6144
	ds_read_b128 v[44:47], v146 offset:6656
	s_waitcnt lgkmcnt(1)
	v_mfma_f32_32x32x16_bf16 v[16:31], v[40:43], v[94:97], v[16:31]
	s_waitcnt lgkmcnt(0)
	v_mfma_f32_32x32x16_bf16 v[0:15], v[44:47], v[94:97], v[0:15]
	ds_read_b128 v[40:43], v146 offset:8192
	ds_read_b128 v[44:47], v146 offset:8704
	s_waitcnt lgkmcnt(1)
	v_mfma_f32_32x32x16_bf16 v[16:31], v[40:43], v[98:101], v[16:31]
	s_waitcnt lgkmcnt(0)
	v_mfma_f32_32x32x16_bf16 v[0:15], v[44:47], v[98:101], v[0:15]
	ds_read_b128 v[40:43], v146 offset:10240
	ds_read_b128 v[44:47], v146 offset:10752
	s_waitcnt lgkmcnt(1)
	v_mfma_f32_32x32x16_bf16 v[16:31], v[40:43], v[102:105], v[16:31]
	v_lshlrev_b32_e32 v40, 8, v145
	v_add3_u32 v147, v33, v40, v32
	s_waitcnt lgkmcnt(0)
	v_mfma_f32_32x32x16_bf16 v[0:15], v[44:47], v[102:105], v[0:15]
	s_nop 7
	v_max_f32_e32 v32, v17, v17
	v_max_f32_e32 v33, v16, v16
	v_max_f32_e32 v32, v33, v32
	s_nop 0
	v_max3_f32 v33, v18, v19, v1
	v_max3_f32 v32, v32, v0, v2
	v_max3_f32 v32, v32, v3, v20
	v_max3_f32 v33, v33, v22, v23
	v_max3_f32 v32, v32, v21, v4
	v_max3_f32 v33, v33, v6, v7
	v_max3_f32 v32, v32, v5, v24
	v_max3_f32 v33, v33, v26, v27
	v_max3_f32 v32, v32, v25, v8
	v_max3_f32 v33, v33, v10, v11
	v_max3_f32 v32, v32, v9, v28
	v_max3_f32 v33, v33, v30, v31
	v_max3_f32 v32, v32, v29, v12
	v_max3_f32 v33, v33, v14, v15
	v_max3_f32 v32, v32, v13, v33
	v_mov_b32_e32 v33, v32
	s_nop 1
	v_permlane32_swap_b32_e32 v32, v33
	v_max_f32_e32 v33, v33, v33
	v_max_f32_e32 v32, v32, v32
	v_max_f32_e32 v32, v32, v33
	v_sub_f32_e32 v16, v16, v32
	v_sub_f32_e32 v0, v0, v32
	v_sub_f32_e32 v17, v17, v32
	v_sub_f32_e32 v1, v1, v32
	v_sub_f32_e32 v18, v18, v32
	v_sub_f32_e32 v2, v2, v32
	v_sub_f32_e32 v19, v19, v32
	v_sub_f32_e32 v3, v3, v32
	v_sub_f32_e32 v20, v20, v32
	v_sub_f32_e32 v4, v4, v32
	v_sub_f32_e32 v21, v21, v32
	v_sub_f32_e32 v5, v5, v32
	v_sub_f32_e32 v22, v22, v32
	v_sub_f32_e32 v6, v6, v32
	v_sub_f32_e32 v23, v23, v32
	v_sub_f32_e32 v7, v7, v32
	v_sub_f32_e32 v24, v24, v32
	v_sub_f32_e32 v8, v8, v32
	v_sub_f32_e32 v25, v25, v32
	v_sub_f32_e32 v9, v9, v32
	v_sub_f32_e32 v26, v26, v32
	v_sub_f32_e32 v10, v10, v32
	v_sub_f32_e32 v27, v27, v32
	v_sub_f32_e32 v11, v11, v32
	v_sub_f32_e32 v28, v28, v32
	v_sub_f32_e32 v12, v12, v32
	v_sub_f32_e32 v29, v29, v32
	v_sub_f32_e32 v13, v13, v32
	v_sub_f32_e32 v30, v30, v32
	v_sub_f32_e32 v14, v14, v32
	v_sub_f32_e32 v31, v31, v32
	v_sub_f32_e32 v15, v15, v32
	v_exp_f32_e32 v106, v16
	v_exp_f32_e32 v74, v0
	v_exp_f32_e32 v107, v17
	v_exp_f32_e32 v75, v1
	v_exp_f32_e32 v112, v18
	v_exp_f32_e32 v110, v2
	v_exp_f32_e32 v113, v19
	v_exp_f32_e32 v111, v3
	v_exp_f32_e32 v108, v20
	v_exp_f32_e32 v78, v4
	v_exp_f32_e32 v109, v21
	v_exp_f32_e32 v79, v5
	v_exp_f32_e32 v76, v22
	v_exp_f32_e32 v72, v6
	v_exp_f32_e32 v77, v23
	v_exp_f32_e32 v73, v7
	v_exp_f32_e32 v70, v24
	v_exp_f32_e32 v68, v8
	v_exp_f32_e32 v71, v25
	v_exp_f32_e32 v69, v9
	v_exp_f32_e32 v66, v26
	v_exp_f32_e32 v64, v10
	v_exp_f32_e32 v67, v27
	v_exp_f32_e32 v65, v11
	v_exp_f32_e32 v46, v28
	v_exp_f32_e32 v44, v12
	v_exp_f32_e32 v47, v29
	v_exp_f32_e32 v45, v13
	v_exp_f32_e32 v42, v30
	v_exp_f32_e32 v40, v14
	v_exp_f32_e32 v43, v31
	v_exp_f32_e32 v41, v15
	v_mov_b32_e32 v0, 0
	v_mov_b32_e32 v1, 0
	v_mov_b32_e32 v2, 0
	v_mov_b32_e32 v3, 0
	v_mov_b32_e32 v4, 0
	v_mov_b32_e32 v5, 0
	v_mov_b32_e32 v6, 0
	v_mov_b32_e32 v7, 0
	v_mov_b32_e32 v8, 0
	v_mov_b32_e32 v9, 0
	v_mov_b32_e32 v10, 0
	v_mov_b32_e32 v11, 0
	v_mov_b32_e32 v12, 0
	v_mov_b32_e32 v13, 0
	v_mov_b32_e32 v14, 0
	v_mov_b32_e32 v15, 0
	v_mov_b32_e32 v16, 0
	v_mov_b32_e32 v17, 0
	v_mov_b32_e32 v18, 0
	v_mov_b32_e32 v19, 0
	v_mov_b32_e32 v20, 0
	v_mov_b32_e32 v21, 0
	v_mov_b32_e32 v22, 0
	v_mov_b32_e32 v23, 0
	v_mov_b32_e32 v24, 0
	v_mov_b32_e32 v25, 0
	v_mov_b32_e32 v26, 0
	v_mov_b32_e32 v27, 0
	v_mov_b32_e32 v28, 0
	v_mov_b32_e32 v29, 0
	v_mov_b32_e32 v30, 0
	v_mov_b32_e32 v31, 0
	v_cvt_pk_bf16_f32 v60, v106, v107
	v_cvt_pk_bf16_f32 v56, v70, v71
	v_cvt_pk_bf16_f32 v52, v74, v75
	v_cvt_pk_bf16_f32 v48, v68, v69
	v_cvt_pk_bf16_f32 v61, v112, v113
	v_cvt_pk_bf16_f32 v57, v66, v67
	v_cvt_pk_bf16_f32 v53, v110, v111
	v_cvt_pk_bf16_f32 v49, v64, v65
	v_cvt_pk_bf16_f32 v62, v108, v109
	v_cvt_pk_bf16_f32 v58, v46, v47
	v_cvt_pk_bf16_f32 v54, v78, v79
	v_cvt_pk_bf16_f32 v50, v44, v45
	v_cvt_pk_bf16_f32 v63, v76, v77
	v_cvt_pk_bf16_f32 v59, v42, v43
	v_cvt_pk_bf16_f32 v55, v72, v73
	v_cvt_pk_bf16_f32 v51, v40, v41
	s_cbranch_vccz .Lmla_apv0
; template <int MODE> __device__ __forceinline__ void attn_unit(const Unit& a, char* shm) {
;     ...
;             if (g == 0) ATT_PV(pw, sv); else pend = true;
	ds_read_b64_tr_b16 v[230:231], v147 offset:24576
	ds_read_b64_tr_b16 v[232:233], v147 offset:25088
	ds_read_b64_tr_b16 v[234:235], v147 offset:25600
	ds_read_b64_tr_b16 v[236:237], v147 offset:26112
	ds_read_b64_tr_b16 v[238:239], v147 offset:26624
	ds_read_b64_tr_b16 v[240:241], v147 offset:27136
	ds_read_b64_tr_b16 v[242:243], v147 offset:27648
	ds_read_b64_tr_b16 v[244:245], v147 offset:28160
	ds_read_b64_tr_b16 v[246:247], v147 offset:28672
	ds_read_b64_tr_b16 v[248:249], v147 offset:29184
	ds_read_b64_tr_b16 v[150:151], v147 offset:29696
	ds_read_b64_tr_b16 v[152:153], v147 offset:30208
	ds_read_b64_tr_b16 v[154:155], v147 offset:30720
	ds_read_b64_tr_b16 v[156:157], v147 offset:31232
	ds_read_b64_tr_b16 v[158:159], v147 offset:31744
	ds_read_b64_tr_b16 v[160:161], v147 offset:32256
	s_branch .LBB0_1909
.Lmla_apv0:
	ds_read_b64_tr_b16 v[0:1], v147 offset:24576
	ds_read_b64_tr_b16 v[2:3], v147 offset:25088
	ds_read_b64_tr_b16 v[16:17], v147 offset:25600
	ds_read_b64_tr_b16 v[18:19], v147 offset:26112
	s_waitcnt lgkmcnt(2)
	v_mfma_f32_32x32x16_bf16 v[0:15], v[60:63], v[0:3], 0
	s_waitcnt lgkmcnt(0)
	v_mfma_f32_32x32x16_bf16 v[0:15], v[56:59], v[16:19], v[0:15]
	ds_read_b64_tr_b16 v[16:17], v147 offset:26624
	ds_read_b64_tr_b16 v[18:19], v147 offset:27136
	s_waitcnt lgkmcnt(0)
	v_mfma_f32_32x32x16_bf16 v[0:15], v[52:55], v[16:19], v[0:15]
	ds_read_b64_tr_b16 v[16:17], v147 offset:27648
	ds_read_b64_tr_b16 v[18:19], v147 offset:28160
	s_waitcnt lgkmcnt(0)
	v_mfma_f32_32x32x16_bf16 v[0:15], v[48:51], v[16:19], v[0:15]
	ds_read_b64_tr_b16 v[16:17], v147 offset:28672
	ds_read_b64_tr_b16 v[18:19], v147 offset:29184
	ds_read_b64_tr_b16 v[114:115], v147 offset:29696
	ds_read_b64_tr_b16 v[116:117], v147 offset:30208
	s_waitcnt lgkmcnt(2)
	v_mfma_f32_32x32x16_bf16 v[16:31], v[60:63], v[16:19], 0
	s_waitcnt lgkmcnt(0)
	v_mfma_f32_32x32x16_bf16 v[16:31], v[56:59], v[114:117], v[16:31]
	ds_read_b64_tr_b16 v[114:115], v147 offset:30720
	ds_read_b64_tr_b16 v[116:117], v147 offset:31232
	s_waitcnt lgkmcnt(0)
	v_mfma_f32_32x32x16_bf16 v[16:31], v[52:55], v[114:117], v[16:31]
	ds_read_b64_tr_b16 v[114:115], v147 offset:31744
	ds_read_b64_tr_b16 v[116:117], v147 offset:32256
	s_waitcnt lgkmcnt(0)
	v_mfma_f32_32x32x16_bf16 v[16:31], v[48:51], v[114:117], v[16:31]

; #define LAS __attribute__((address_space(3)))
; __device__ __forceinline__ int crow(int r, int hi) { return (r & 3) + 8 * (r >> 2) + 4 * hi; }
; #define MX3(a_, b_, c_) __builtin_fmaxf(__builtin_fmaxf((a_), (b_)), (c_))
; template <int MODE> __device__ __forceinline__ void attn_unit(const Unit& a, char* shm) {
;     ...
;         if (pend) { ATT_PV(pw, svp); pend = false; }
;         bool active = true;
;         if (MODE == 1) active = (64 * t + 63 >= tq0 - 128) && (64 * t <= tq0 + 31 + 128);
;         if (active) {
;             const lds_cptr kp = shm3 + LDS_K + s * KSLOT + hi * 1024 + r32 * 16;
;             f32x16 p0 = negm, p1 = negm;
; #pragma unroll
;             for (int d0 = 0; d0 < ND; ++d0) {
;                 const bf16x8 b0 = *(const LAS bf16x8*)(kp + d0 * 2048), b1 = *(const LAS bf16x8*)(kp + d0 * 2048 + 512);
;                 p0 = __builtin_amdgcn_mfma_f32_32x32x16_bf16(b0, qr[d0], p0, 0, 0, 0);
;                 p1 = __builtin_amdgcn_mfma_f32_32x32x16_bf16(b1, qr[d0], p1, 0, 0, 0);
;             }
;             if (MODE == 1) {
; #pragma unroll
;                 for (int r = 0; r < 16; ++r) { const int ks = 64 * t + crow(r, hi); const int r0 = abs(tq - ks), r1 = abs(tq - ks - 32);
;                     p0[r] = (r0 <= 128) ? p0[r] - a.slope2 * (float)r0 : -INFINITY; p1[r] = (r1 <= 128) ? p1[r] - a.slope2 * (float)r1 : -INFINITY; }
;             }
;     ...
;             float ra = MX3(p0[0], p0[1], p1[0]), rb = MX3(p0[2], p0[3], p1[1]); ra = MX3(ra, p1[2], p1[3]);
; #pragma unroll
;             for (int r = 4; r < 16; r += 4) { ra = MX3(ra, p0[r], p0[r + 1]); rb = MX3(rb, p0[r + 2], p0[r + 3]); ra = MX3(ra, p1[r], p1[r + 1]); rb = MX3(rb, p1[r + 2], p1[r + 3]); }
;     ...
;             float rm = halfmax(__builtin_fmaxf(ra, rb));
;             const bool first = (MODE == 0) && (t == a.t_lo);
;             if (first || __any(rm > THR)) {
;                 const float dl = first ? rm : fmaxf(rm, 0.f);
;                 mhat += dl;
; #pragma unroll
;                 for (int r = 0; r < 16; ++r) { p0[r] -= dl; p1[r] -= dl; negm[r] = -mhat; }
;                 if (!first) {
;                     const float f = __builtin_amdgcn_exp2f(-dl); l_reg *= f;
;                     if (hi == 0) wsf[r32] = f;
; #pragma unroll
;                     for (int r = 0; r < 16; ++r) { const float fr_ = wsf[crow(r, hi)]; o[0][r] *= fr_; o[1][r] *= fr_; }
;                 }
;             }
.LBB0_1914:
	s_mulk_i32 s34, 0x3000
	v_add_u32_e32 v118, s34, v146
	ds_read_b128 v[182:185], v118
	ds_read_b128 v[186:189], v118 offset:512
	ds_read_b128 v[190:193], v118 offset:2048
	ds_read_b128 v[194:197], v118 offset:2560
	ds_read_b128 v[198:201], v118 offset:4096
	ds_read_b128 v[202:205], v118 offset:4608
	ds_read_b128 v[206:209], v118 offset:6144
	ds_read_b128 v[210:213], v118 offset:6656
	ds_read_b128 v[214:217], v118 offset:8192
	ds_read_b128 v[218:221], v118 offset:8704
	ds_read_b128 v[222:225], v118 offset:10240
	ds_read_b128 v[226:229], v118 offset:10752
	v_lshl_add_u32 v149, s51, 13, v147
	s_andn2_b64 vcc, exec, s[2:3]
	s_cbranch_vccnz .LBB0_1916
	v_mfma_f32_32x32x16_bf16 v[0:15], v[60:63], v[230:233], v[0:15]
	v_mfma_f32_32x32x16_bf16 v[0:15], v[56:59], v[234:237], v[0:15]
	v_mfma_f32_32x32x16_bf16 v[0:15], v[52:55], v[238:241], v[0:15]
	v_mfma_f32_32x32x16_bf16 v[0:15], v[48:51], v[242:245], v[0:15]
	v_mfma_f32_32x32x16_bf16 v[16:31], v[60:63], v[246:249], v[16:31]
	v_mfma_f32_32x32x16_bf16 v[16:31], v[56:59], v[150:153], v[16:31]
	v_mfma_f32_32x32x16_bf16 v[16:31], v[52:55], v[154:157], v[16:31]
	v_mfma_f32_32x32x16_bf16 v[16:31], v[48:51], v[158:161], v[16:31]
.LBB0_1916:
	s_waitcnt lgkmcnt(11)
	v_mfma_f32_32x32x16_bf16 v[48:63], v[182:185], v[82:85], v[32:47]
	s_waitcnt lgkmcnt(10)
	v_mfma_f32_32x32x16_bf16 v[64:79], v[186:189], v[82:85], v[32:47]
	s_waitcnt lgkmcnt(9)
	v_mfma_f32_32x32x16_bf16 v[48:63], v[190:193], v[86:89], v[48:63]
	s_waitcnt lgkmcnt(8)
	v_mfma_f32_32x32x16_bf16 v[64:79], v[194:197], v[86:89], v[64:79]
	s_waitcnt lgkmcnt(7)
	v_mfma_f32_32x32x16_bf16 v[48:63], v[198:201], v[90:93], v[48:63]
	s_waitcnt lgkmcnt(6)
	v_mfma_f32_32x32x16_bf16 v[64:79], v[202:205], v[90:93], v[64:79]
	s_waitcnt lgkmcnt(5)
	v_mfma_f32_32x32x16_bf16 v[48:63], v[206:209], v[94:97], v[48:63]
	s_waitcnt lgkmcnt(4)
	v_mfma_f32_32x32x16_bf16 v[64:79], v[210:213], v[94:97], v[64:79]
	s_waitcnt lgkmcnt(3)
	v_mfma_f32_32x32x16_bf16 v[48:63], v[214:217], v[98:101], v[48:63]
	s_waitcnt lgkmcnt(2)
	v_mfma_f32_32x32x16_bf16 v[64:79], v[218:221], v[98:101], v[64:79]
	s_waitcnt lgkmcnt(1)
	v_mfma_f32_32x32x16_bf16 v[48:63], v[222:225], v[102:105], v[48:63]
	s_waitcnt lgkmcnt(0)
	v_mfma_f32_32x32x16_bf16 v[64:79], v[226:229], v[102:105], v[64:79]
	ds_read_b64_tr_b16 v[230:231], v149 offset:24576
	ds_read_b64_tr_b16 v[232:233], v149 offset:25088
	ds_read_b64_tr_b16 v[234:235], v149 offset:25600
	ds_read_b64_tr_b16 v[236:237], v149 offset:26112
	ds_read_b64_tr_b16 v[238:239], v149 offset:26624
	ds_read_b64_tr_b16 v[240:241], v149 offset:27136
	ds_read_b64_tr_b16 v[242:243], v149 offset:27648
	ds_read_b64_tr_b16 v[244:245], v149 offset:28160
	ds_read_b64_tr_b16 v[246:247], v149 offset:28672
	ds_read_b64_tr_b16 v[248:249], v149 offset:29184
	ds_read_b64_tr_b16 v[150:151], v149 offset:29696
	ds_read_b64_tr_b16 v[152:153], v149 offset:30208
	ds_read_b64_tr_b16 v[154:155], v149 offset:30720
	ds_read_b64_tr_b16 v[156:157], v149 offset:31232
	v_max_f32_e32 v118, v49, v49
	v_max_f32_e32 v119, v48, v48
	v_max_f32_e32 v118, v119, v118
	v_max3_f32 v114, v50, v51, v65
	v_max3_f32 v115, v118, v64, v66
	v_max3_f32 v115, v115, v67, v52
	v_max3_f32 v114, v114, v54, v55
	v_max3_f32 v115, v115, v53, v68
	v_max3_f32 v114, v114, v70, v71
	v_max3_f32 v115, v115, v69, v56
	v_max3_f32 v114, v114, v58, v59
	v_max3_f32 v115, v115, v57, v72
	v_max3_f32 v114, v114, v74, v75
	v_max3_f32 v115, v115, v73, v60
	v_max3_f32 v114, v114, v62, v63
	v_max3_f32 v115, v115, v61, v76
	v_max3_f32 v114, v114, v78, v79
	v_max3_f32 v114, v115, v77, v114
	v_mov_b32_e32 v115, v114
	s_nop 1
	v_permlane32_swap_b32_e32 v114, v115
	v_max_f32_e32 v115, v115, v115
	v_max_f32_e32 v114, v114, v114
	v_max_f32_e32 v114, v114, v115
	v_cmp_lt_f32_e32 vcc, s19, v114
	s_cbranch_vccz .LBB0_1920
	v_max_f32_e32 v32, v114, v114
	v_max_f32_e32 v32, 0, v32
	v_exp_f32_e64 v33, -v32
	s_and_saveexec_b64 s[46:47], s[42:43]
	ds_write_b32 v148, v33 offset:49152
	s_or_b64 exec, exec, s[46:47]
	v_pk_add_f32 v[114:115], v[112:113], v[32:33]
	v_pk_mul_f32 v[40:41], v[112:113], v[32:33]
	v_add_u32_e32 v44, s49, v80
	v_pk_add_f32 v[48:49], v[48:49], v[32:33] op_sel_hi:[1,0] neg_lo:[0,1] neg_hi:[0,1]
	v_pk_add_f32 v[64:65], v[64:65], v[32:33] op_sel_hi:[1,0] neg_lo:[0,1] neg_hi:[0,1]
	v_pk_add_f32 v[50:51], v[50:51], v[32:33] op_sel_hi:[1,0] neg_lo:[0,1] neg_hi:[0,1]
	v_pk_add_f32 v[66:67], v[66:67], v[32:33] op_sel_hi:[1,0] neg_lo:[0,1] neg_hi:[0,1]
	v_pk_add_f32 v[52:53], v[52:53], v[32:33] op_sel_hi:[1,0] neg_lo:[0,1] neg_hi:[0,1]
	v_pk_add_f32 v[68:69], v[68:69], v[32:33] op_sel_hi:[1,0] neg_lo:[0,1] neg_hi:[0,1]
	v_pk_add_f32 v[54:55], v[54:55], v[32:33] op_sel_hi:[1,0] neg_lo:[0,1] neg_hi:[0,1]
	v_pk_add_f32 v[70:71], v[70:71], v[32:33] op_sel_hi:[1,0] neg_lo:[0,1] neg_hi:[0,1]
	v_pk_add_f32 v[56:57], v[56:57], v[32:33] op_sel_hi:[1,0] neg_lo:[0,1] neg_hi:[0,1]
	v_pk_add_f32 v[72:73], v[72:73], v[32:33] op_sel_hi:[1,0] neg_lo:[0,1] neg_hi:[0,1]
	v_pk_add_f32 v[58:59], v[58:59], v[32:33] op_sel_hi:[1,0] neg_lo:[0,1] neg_hi:[0,1]
	v_pk_add_f32 v[74:75], v[74:75], v[32:33] op_sel_hi:[1,0] neg_lo:[0,1] neg_hi:[0,1]
	v_pk_add_f32 v[60:61], v[60:61], v[32:33] op_sel_hi:[1,0] neg_lo:[0,1] neg_hi:[0,1]
	v_pk_add_f32 v[76:77], v[76:77], v[32:33] op_sel_hi:[1,0] neg_lo:[0,1] neg_hi:[0,1]
	v_pk_add_f32 v[62:63], v[62:63], v[32:33] op_sel_hi:[1,0] neg_lo:[0,1] neg_hi:[0,1]
	v_pk_add_f32 v[78:79], v[78:79], v[32:33] op_sel_hi:[1,0] neg_lo:[0,1] neg_hi:[0,1]
	ds_read_b128 v[32:35], v44 offset:49216
	ds_read_b128 v[36:39], v44 offset:49248
	v_mov_b32_e32 v115, v41
	ds_read_b128 v[40:43], v44 offset:49152
	ds_read_b128 v[116:119], v44 offset:49184
	v_pk_add_f32 v[46:47], v[114:115], 0 neg_lo:[1,1] neg_hi:[1,1]
	s_waitcnt lgkmcnt(3)
	v_pk_mul_f32 v[26:27], v[26:27], v[34:35]
	s_waitcnt lgkmcnt(2)
	v_pk_mul_f32 v[30:31], v[30:31], v[38:39]
	v_pk_mul_f32 v[28:29], v[28:29], v[36:37]
	v_pk_mul_f32 v[24:25], v[24:25], v[32:33]
	s_waitcnt lgkmcnt(0)
	v_pk_mul_f32 v[22:23], v[22:23], v[118:119]
	v_pk_mul_f32 v[20:21], v[20:21], v[116:117]
	v_pk_mul_f32 v[18:19], v[18:19], v[42:43]
	v_pk_mul_f32 v[16:17], v[16:17], v[40:41]
	v_pk_mul_f32 v[14:15], v[14:15], v[38:39]
	v_pk_mul_f32 v[12:13], v[12:13], v[36:37]
	v_pk_mul_f32 v[10:11], v[10:11], v[34:35]
	v_pk_mul_f32 v[8:9], v[8:9], v[32:33]
	v_pk_mul_f32 v[6:7], v[6:7], v[118:119]
	v_pk_mul_f32 v[4:5], v[4:5], v[116:117]
	v_pk_mul_f32 v[2:3], v[2:3], v[42:43]
	v_pk_mul_f32 v[0:1], v[0:1], v[40:41]
	v_mov_b32_e32 v47, v46
	v_mov_b32_e32 v45, v46
	v_mov_b32_e32 v44, v46
	v_mov_b32_e32 v43, v46
	v_mov_b32_e32 v42, v46
	v_mov_b32_e32 v41, v46
	v_mov_b32_e32 v40, v46
	v_mov_b32_e32 v39, v46
	v_mov_b32_e32 v38, v46
	v_mov_b32_e32 v37, v46
	v_mov_b32_e32 v36, v46
	v_mov_b32_e32 v35, v46
	v_mov_b32_e32 v34, v46
	v_mov_b32_e32 v33, v46
	v_mov_b32_e32 v32, v46
	v_mov_b64_e32 v[112:113], v[114:115]
; __device__ __forceinline__ unsigned cvt_pk_bf16(float lo, float hi) { unsigned r; asm volatile("v_cvt_pk_bf16_f32 %0, %1, %2" : "=v"(r) : "v"(lo), "v"(hi)); return r; }
; template <int MODE> __device__ __forceinline__ void attn_unit(const Unit& a, char* shm) {
;     ...
; #pragma unroll
;             for (int r = 0; r < 16; ++r) { p0[r] = __builtin_amdgcn_exp2f(p0[r]); p1[r] = __builtin_amdgcn_exp2f(p1[r]); }
;             f32x2 s2a = (f32x2){p0[0], p0[1]}, s2b = (f32x2){p1[0], p1[1]};
; #pragma unroll
;             for (int k2 = 1; k2 < 8; ++k2) { s2a += (f32x2){p0[2 * k2], p0[2 * k2 + 1]}; s2b += (f32x2){p1[2 * k2], p1[2 * k2 + 1]}; }
;             s2a += s2b;
;             l_reg += s2a.x + s2a.y;
; #pragma unroll
;             for (int kk = 0; kk < 4; ++kk) { pw[0][kk] = cvt_pk_bf16(p0[2 * kk], p0[2 * kk + 1]); pw[1][kk] = cvt_pk_bf16(p0[8 + 2 * kk], p0[8 + 2 * kk + 1]);
;                 pw[2][kk] = cvt_pk_bf16(p1[2 * kk], p1[2 * kk + 1]); pw[3][kk] = cvt_pk_bf16(p1[8 + 2 * kk], p1[8 + 2 * kk + 1]); }
;             if (g == 0) ATT_PV(pw, sv); else pend = true;
.LBB0_1920:
	ds_read_b64_tr_b16 v[158:159], v149 offset:31744
	ds_read_b64_tr_b16 v[160:161], v149 offset:32256
	v_exp_f32_e32 v128, v48
	v_exp_f32_e32 v122, v64
	v_exp_f32_e32 v129, v49
	v_exp_f32_e32 v123, v65
	v_exp_f32_e32 v140, v50
	v_exp_f32_e32 v138, v66
	v_exp_f32_e32 v141, v51
	v_exp_f32_e32 v139, v67
	v_exp_f32_e32 v136, v52
	v_exp_f32_e32 v126, v68
	v_exp_f32_e32 v137, v53
	v_exp_f32_e32 v127, v69
	v_exp_f32_e32 v124, v54
	v_exp_f32_e32 v120, v70
	v_exp_f32_e32 v125, v55
	v_exp_f32_e32 v121, v71
	v_exp_f32_e32 v118, v56
	v_exp_f32_e32 v116, v72
	v_exp_f32_e32 v119, v57
	v_exp_f32_e32 v117, v73
	v_exp_f32_e32 v114, v58
	v_exp_f32_e32 v72, v74
	v_exp_f32_e32 v115, v59
	v_exp_f32_e32 v73, v75
	v_exp_f32_e32 v70, v60
	v_exp_f32_e32 v68, v76
	v_exp_f32_e32 v71, v61
	v_exp_f32_e32 v69, v77
	v_exp_f32_e32 v66, v62
	v_exp_f32_e32 v64, v78
	v_exp_f32_e32 v67, v63
	v_exp_f32_e32 v65, v79
	s_andn2_b64 vcc, exec, s[44:45]
	v_cvt_pk_bf16_f32 v60, v128, v129
	v_cvt_pk_bf16_f32 v56, v118, v119
	v_cvt_pk_bf16_f32 v52, v122, v123
	v_cvt_pk_bf16_f32 v48, v116, v117
	v_cvt_pk_bf16_f32 v61, v140, v141
	v_cvt_pk_bf16_f32 v57, v114, v115
	v_cvt_pk_bf16_f32 v53, v138, v139
	v_cvt_pk_bf16_f32 v49, v72, v73
	v_cvt_pk_bf16_f32 v62, v136, v137
	v_cvt_pk_bf16_f32 v58, v70, v71
	v_cvt_pk_bf16_f32 v54, v126, v127
	v_cvt_pk_bf16_f32 v50, v68, v69
	v_cvt_pk_bf16_f32 v63, v124, v125
	v_cvt_pk_bf16_f32 v59, v66, v67
	v_cvt_pk_bf16_f32 v55, v120, v121
	v_cvt_pk_bf16_f32 v51, v64, v65
	s_cbranch_vccnz .LBB0_1922
	s_waitcnt lgkmcnt(0)
	v_mfma_f32_32x32x16_bf16 v[0:15], v[60:63], v[230:233], v[0:15]
	v_mfma_f32_32x32x16_bf16 v[0:15], v[56:59], v[234:237], v[0:15]
	v_mfma_f32_32x32x16_bf16 v[0:15], v[52:55], v[238:241], v[0:15]
	v_mfma_f32_32x32x16_bf16 v[0:15], v[48:51], v[242:245], v[0:15]
	v_mfma_f32_32x32x16_bf16 v[16:31], v[60:63], v[246:249], v[16:31]
	v_mfma_f32_32x32x16_bf16 v[16:31], v[56:59], v[150:153], v[16:31]
	v_mfma_f32_32x32x16_bf16 v[16:31], v[52:55], v[154:157], v[16:31]
	v_mfma_f32_32x32x16_bf16 v[16:31], v[48:51], v[158:161], v[16:31]

; template <int MODE> __device__ __forceinline__ void attn_unit(const Unit& a, char* shm) {
;     ...
;     if (pend) ATT_PV(pw, svp);
.LBB0_1924:
	s_and_b64 vcc, exec, s[2:3]
	s_cbranch_vccz .LBB0_1926
	s_waitcnt lgkmcnt(0)
	v_mfma_f32_32x32x16_bf16 v[0:15], v[60:63], v[230:233], v[0:15]
	v_mfma_f32_32x32x16_bf16 v[0:15], v[56:59], v[234:237], v[0:15]
	v_mfma_f32_32x32x16_bf16 v[0:15], v[52:55], v[238:241], v[0:15]
	v_mfma_f32_32x32x16_bf16 v[0:15], v[48:51], v[242:245], v[0:15]
	v_mfma_f32_32x32x16_bf16 v[16:31], v[60:63], v[246:249], v[16:31]
	v_mfma_f32_32x32x16_bf16 v[16:31], v[56:59], v[150:153], v[16:31]
	v_mfma_f32_32x32x16_bf16 v[16:31], v[52:55], v[154:157], v[16:31]
	v_mfma_f32_32x32x16_bf16 v[16:31], v[48:51], v[158:161], v[16:31]
